# lever 4: one static s_setprio 1 for the odd hardware wave slot (s_getreg HW_ID) during the P2 and P5 GEMM mainloops
# speedup vs baseline: 1.0036x; 1.0036x over previous
; template <int NI>
; DI void p2_store_group(const Params& p, const f32x16 (&a)[NI], int colg, int tok0, int b, int h) {
;   if (colg >= INC) return;
;   bf16_t* base; int stride, mode = 0, use_s = 0; float scale = 1.f;
;   if (colg < 1536) {
;     const int which = colg >> 9, hh = (colg & 511) >> 6, d0 = colg & 63;
;     base = (which == 0 ? p.Qsb : (which == 1 ? p.Ksb : p.Vsb)) + (size_t)(b * 8 + hh) * S_ * 64 + d0; stride = 64; use_s = 1;
;     if (which == 0) scale = 0.125f * LOG2E;
;   } else if (colg < 2048) { base = p.Gate + (colg - 1536); stride = 1024; mode = 1; }
;   else if (colg < 2432) { base = p.CQ + (colg - 2048); stride = 384; }
;   else if (colg < 2688) { base = p.CKV + (colg - 2432); stride = 256; }
;   else if (colg < 2720) { base = nullptr; stride = 32; mode = 2; }
;   else { base = p.Gate + 512 + (colg - 2720); stride = 1024; mode = 1; }
; DI void phase2(const Params& p, char* smem, const Sched sc) {
;   const int tid = threadIdx.x, lane = tid & 63, wave = tid >> 6, r = lane & 31, h = lane >> 5, wr = wave >> 1, wc = wave & 1;
;   constexpr int NFULL = 384, NLIST = 16 * 26;
;   u32x4 rr[2][4], cr[2][4];
;   for (int v = sc.xi; v < 8; v += sc.nx) {
;     bool cold = true;
;     for (int l = sc.rank; l < NFULL; l += sc.nloc) {
;       const int g8 = l / (8 * 26), rem = l % (8 * 26), nt = rem >> 3, mt = 16 * v + 8 * g8 + (rem & 7), m0 = mt * 128, n0 = nt * 128;
;       const int l2 = l + sc.nloc;
;       long dR = 0, dC = 0;
;       if (l2 < NFULL) {
;         const int g8n = l2 / (8 * 26), remn = l2 % (8 * 26), ntn = remn >> 3, mtn = 16 * v + 8 * g8n + (remn & 7);
;         dR = (long)(ntn * 128 - n0) * DM; dC = (long)(mtn * 128 - m0) * DM;
;       }
;       f32x16 acc[2][2];
;       gemm_tile_core<128, 128, 2, 2, false, 64, true>(p.WinT + (size_t)n0 * DM, DM, p.H + (size_t)m0 * DM, DM, DM, smem, acc, nullptr, rr, cr, dR, dC, cold);
.LBB0_180:
	s_or_b64 exec, exec, s[2:3]
	v_cndmask_b32_e64 v0, 0, 1, s[0:1]
	v_cmp_ne_u32_e64 s[2:3], 1, v0
	v_bfe_u32 v171, v241, 5, 1
	s_andn2_b64 vcc, exec, s[0:1]
	v_writelane_b32 v255, s2, 5
	v_and_b32_e32 v226, 31, v241
	v_lshlrev_b32_e32 v214, 4, v241
	v_writelane_b32 v255, s3, 6
	v_lshrrev_b32_e32 v213, 1, v241
	v_lshlrev_b32_e32 v180, 3, v171
	v_lshlrev_b32_e32 v178, 4, v171
	s_barrier
	s_cbranch_vccnz .LBB0_335
	s_getreg_b32 s4, hwreg(HW_REG_HW_ID, 0, 4)
	s_bitcmp1_b32 s4, 0
	s_cbranch_scc0 .Lp2_noprio
	s_setprio 1
.Lp2_noprio:
	v_and_b32_e32 v158, 0x1c0, v213
	s_movk_i32 s4, 0x90
	v_or_b32_e32 v1, v158, v226
	v_lshrrev_b32_e32 v2, 2, v241
	v_and_b32_e32 v3, 16, v213
	s_movk_i32 s5, 0xc0
	v_mad_u32_u24 v160, v1, s4, v3
	v_and_or_b32 v1, v2, s5, v226
	s_movk_i32 s5, 0x60
	v_and_or_b32 v2, v213, s5, v226
	v_and_b32_e32 v0, 0x70, v214
	v_and_b32_e32 v159, 0x5f, v241
	v_add_u32_e32 v2, 64, v2
	v_mad_u32_u24 v157, v232, s4, v0
	v_mad_u32_u24 v161, v159, s4, v3
	v_mad_u32_u24 v162, v1, s4, v3
	v_mad_u32_u24 v163, v2, s4, v3
	s_load_dwordx2 s[4:5], s[68:69], 0x98
	s_movk_i32 s6, 0x1e0
	v_and_or_b32 v164, v213, s6, v226
	s_load_dwordx2 s[6:7], s[68:69], 0xb8
	s_load_dwordx8 s[12:19], s[68:69], 0xd8
	v_lshlrev_b32_e32 v144, 11, v232
	v_mov_b32_e32 v145, 0
	s_cmpk_lt_i32 s75, 0x180
	s_waitcnt lgkmcnt(0)
	v_lshl_add_u64 v[2:3], s[4:5], 0, v[144:145]
	v_mov_b32_e32 v1, v145
	s_cselect_b64 s[2:3], -1, 0
	v_lshl_add_u64 v[146:147], v[2:3], 0, v[0:1]
	v_lshl_add_u64 v[2:3], s[6:7], 0, v[144:145]
	v_mov_b32_e32 v179, v145
	s_cmp_lt_i32 s75, 64
	v_lshl_add_u64 v[148:149], v[2:3], 0, v[0:1]
	v_lshl_add_u64 v[150:151], s[18:19], 0, v[178:179]
	v_cndmask_b32_e64 v0, 0, 1, s[2:3]
	s_movk_i32 s10, 0xeec0
	s_movk_i32 s18, 0xed00
	s_movk_i32 s20, 0xf000
	s_movk_i32 s22, 0xf400
	s_movk_i32 s24, 0xef00
	s_movk_i32 s26, 0xed40
	s_movk_i32 s28, 0xf040
	s_movk_i32 s30, 0xf440
	s_cselect_b64 s[0:1], -1, 0
	v_add_u32_e32 v165, 0xd800, v157
	v_cmp_ne_u32_e64 s[6:7], 1, v0
	s_lshl_b32 s50, s75, 4
	s_lshl_b32 s51, s33, 4
	s_mov_b32 s52, 0x10000
	s_mov_b32 s5, 0
	s_mov_b32 s53, 0x20000
	s_mov_b32 s54, 0x30000
	s_movk_i32 s55, 0x200
	s_movk_i32 s56, 0xd0
	s_movk_i32 s57, 0x1fff
	s_movk_i32 s58, 0xca0
	s_movk_i32 s59, 0x5ff
	s_movk_i32 s60, 0x600
	s_movk_i32 s61, 0x7ff
	s_movk_i32 s62, 0x97f
	s_movk_i32 s63, 0xa7f
	s_movk_i32 s64, 0xa9f
	s_mov_b32 s11, -1
	s_mov_b32 s19, -1
	s_mov_b32 s21, -1
	s_mov_b32 s23, -1
	s_mov_b32 s25, -1
	s_mov_b32 s27, -1
	s_mov_b32 s29, -1
	s_mov_b32 s31, -1
	v_mov_b32_e32 v166, 0xd0
	v_mov_b32_e32 v167, 0xc8
	v_mov_b32_e32 v168, 0x1fdf
	v_mov_b32_e32 v169, 0xc0
	v_mov_b32_e32 v170, 0x3e38aa3b
	s_mov_b32 s65, s76
	s_branch .LBB0_183

; DI unsigned xb_ld(unsigned* p) { return __hip_atomic_load(p, __ATOMIC_RELAXED, __HIP_MEMORY_SCOPE_AGENT); }
; DI unsigned xb_add(unsigned* p, unsigned v) { return __hip_atomic_fetch_add(p, v, __ATOMIC_RELAXED, __HIP_MEMORY_SCOPE_AGENT); }
; #define XB_SPIN(cond, bar) do { unsigned _sp = 0; while (cond) { __builtin_amdgcn_s_sleep(1); \
;     if ((++_sp & 255u) == 0u) { if (xb_ld(&(bar)[XB_TMO])) break; if (_sp > XB_SPIN_CAP) { atomicAdd(&(bar)[XB_TMO], 1u); break; } } } } while (0)
; DI void xcd_local_barrier(const XcdBarrier& b) {
;   asm volatile("s_waitcnt vmcnt(0)" ::: "memory");
;   __syncthreads();
;   if (threadIdx.x == 0) {
;     unsigned* bar = b.bar;
;     __builtin_amdgcn_s_waitcnt(0);
;     const unsigned nloc = b.st[0];
;     const unsigned old = xb_add(&bar[XB_LSUB(b.x)], 1u);
;     const unsigned gen = old / nloc;
;     if (old + 1u == (gen + 1u) * nloc) xb_add(&bar[XB_LGEN(b.x)], 1u);
;     else XB_SPIN(xb_ld(&bar[XB_LGEN(b.x)]) == gen, bar);
.LBB0_335:
	s_setprio 0
	s_waitcnt vmcnt(0)
	s_barrier
	s_and_saveexec_b64 s[0:1], s[72:73]
	s_cbranch_execz .LBB0_353
	v_mov_b32_e32 v0, 0x12400
	s_waitcnt vmcnt(0) expcnt(0) lgkmcnt(0)
	ds_read_b32 v0, v0
	s_mov_b64 s[4:5], exec
	v_readlane_b32 s2, v255, 4
	s_lshl_b32 s2, s2, 8
	v_mbcnt_lo_u32_b32 v1, s4, 0
	s_add_u32 s2, s70, s2
	v_mbcnt_hi_u32_b32 v1, s5, v1
	s_addc_u32 s3, s71, 0
	v_cmp_eq_u32_e32 vcc, 0, v1
	s_and_saveexec_b64 s[6:7], vcc
	s_cbranch_execz .LBB0_338
	s_bcnt1_i32_b64 s4, s[4:5]
	v_mov_b32_e32 v2, 0x4000
	v_mov_b32_e32 v3, s4
	global_atomic_add v2, v2, v3, s[2:3] sc0

; DI void phase5(const Params& p, char* smem, const Sched sc) {
;   const int tid = threadIdx.x, lane = tid & 63, wave = tid >> 6, r = lane & 31, h = lane >> 5, wr = wave >> 1, wc = wave & 1;
;   constexpr int CST = 132;
;   float* ct = (float*)smem;
;   for (int v = sc.xi; v < 8; v += sc.nx)
;   for (int l = sc.rank; l < 16 * 8; l += sc.nloc) {
;     const int g8 = l >> 6, rem = l & 63, nt = rem >> 3, mt = 16 * v + 8 * g8 + (rem & 7), m0 = mt * 128, n0 = nt * 128;
;     f32x16 acc[2][2];
;     gemm_tile<128, 128, 2, 2, false, true>(p.WoutT + (size_t)n0 * DM, DM, p.Mixed + (size_t)m0 * DM, DM, DM, smem, acc, nullptr);
.LBB0_524:
	s_or_b64 exec, exec, s[0:1]
	v_readlane_b32 s0, v255, 5
	v_readlane_b32 s1, v255, 6
	s_and_b64 vcc, exec, s[0:1]
	s_waitcnt lgkmcnt(0)
	s_barrier
	s_cbranch_vccnz .LBB0_530
	s_getreg_b32 s2, hwreg(HW_REG_HW_ID, 0, 4)
	s_bitcmp1_b32 s2, 0
	s_cbranch_scc0 .Lp5_noprio
	s_setprio 1
.Lp5_noprio:
	v_and_b32_e32 v1, 0x1c0, v213
	v_and_b32_e32 v0, 0x70, v214
	s_movk_i32 s2, 0x90
	v_and_or_b32 v2, v241, 31, v1
	v_and_b32_e32 v3, 0x5f, v241
	v_and_b32_e32 v4, 16, v213
	s_waitcnt vmcnt(2)
	v_mad_u32_u24 v120, v232, s2, v0
	v_mad_u32_u24 v121, v2, s2, v4
	v_mad_u32_u24 v122, v3, s2, v4
	s_load_dwordx2 s[2:3], s[68:69], 0xb0
	s_load_dwordx2 s[8:9], s[68:69], 0x110
	v_lshlrev_b32_e32 v96, 11, v232
	v_mov_b32_e32 v97, 0
	v_lshl_or_b32 v8, v1, 2, v4
	s_waitcnt lgkmcnt(0)
	v_lshl_add_u64 v[6:7], s[2:3], 0, v[96:97]
	s_load_dwordx4 s[4:7], s[68:69], 0x70
	s_load_dwordx2 s[2:3], s[68:69], 0x0
	v_lshlrev_b32_e32 v1, 2, v241
	s_cmpk_lt_i32 s75, 0x80
	v_and_b32_e32 v2, 0x7c, v1
	v_mov_b32_e32 v1, v97
	s_cselect_b64 s[0:1], -1, 0
	s_waitcnt vmcnt(1)
	v_lshrrev_b32_e32 v124, 5, v241
	v_lshl_add_u64 v[98:99], v[6:7], 0, v[0:1]
	v_lshl_add_u64 v[6:7], s[8:9], 0, v[96:97]
	v_lshlrev_b32_e32 v4, 2, v2
	v_mul_u32_u24_e32 v3, 0x210, v3
	v_mul_u32_u24_e32 v9, 0x210, v124
	v_lshl_add_u64 v[100:101], v[6:7], 0, v[0:1]
	v_mov_b32_e32 v5, v97
	v_cndmask_b32_e64 v0, 0, 1, s[0:1]
	v_add_u32_e32 v123, 0xd800, v120
	v_add_u32_e32 v125, 8, v124
	v_add_u32_e32 v126, 16, v124
	v_add_u32_e32 v127, 24, v124
	s_waitcnt vmcnt(0)
	v_or_b32_e32 v128, 32, v124
	v_add_u32_e32 v129, 40, v124
	v_add_u32_e32 v130, 48, v124
	v_add_u32_e32 v131, 56, v124
	v_or_b32_e32 v132, 64, v124
	v_add_u32_e32 v133, 0x48, v124
	v_add_u32_e32 v134, 0x50, v124
	v_add_u32_e32 v135, 0x58, v124
	v_or_b32_e32 v136, 0x60, v124
	v_add_u32_e32 v137, 0x68, v124
	v_add_u32_e32 v138, 0x70, v124
	v_add_u32_e32 v139, 0x78, v124
	s_waitcnt lgkmcnt(0)
	v_lshl_add_u64 v[102:103], s[2:3], 0, v[4:5]
	s_lshl_b32 s10, s75, 4
	s_lshl_b32 s11, s33, 4
	v_cmp_ne_u32_e64 s[0:1], 1, v0
	s_mov_b32 s3, 0
	s_mov_b32 s12, 0x10000
	s_mov_b32 s13, 0x20000
	s_mov_b32 s14, 0x30000
	v_add_u32_e32 v140, v8, v3
	v_lshlrev_b32_e32 v96, 2, v2
	s_movk_i32 s15, 0x2000
	s_mov_b32 s16, 0x8000
	s_mov_b32 s17, 0x18000
	s_mov_b32 s18, 0x28000
	s_mov_b32 s19, 0x38000
	v_add_u32_e32 v141, v4, v9
	s_mov_b32 s20, 0x48000
	s_mov_b32 s21, 0x50000
	s_mov_b32 s22, 0x58000
	s_branch .LBB0_527
